# NSA window loop: in-body vmcnt waits (Q fragments, already covered by the loop-head wait) no longer drain the LDS-DMA prefetch each iteration
# baseline (speedup 1.0000x reference)
.LBB0_1223:
	s_add_i32 s6, s26, 0
	s_cmp_le_u32 s27, s54
	s_cselect_b64 s[10:11], -1, 0
	s_xor_b64 s[12:13], s[28:29], -1
	s_or_b64 s[48:49], s[10:11], s[12:13]
	v_add_u32_e32 v91, 0xfffffdfb, v110
	v_add_u32_e32 v90, 0xfffffdfa, v110
	v_add_u32_e32 v89, 0xfffffdf9, v110
	v_add_u32_e32 v88, 0xfffffddc, v110
	v_add_u32_e32 v87, 0xfffffddb, v110
	v_add_u32_e32 v86, 0xfffffdda, v110
	v_add_u32_e32 v85, 0xfffffdd9, v110
	s_mov_b64 s[52:53], -1
	s_and_b64 vcc, exec, s[48:49]
	v_cmp_ge_f32_e64 s[28:29], s76, v92
	v_add_u32_e32 v84, s6, v163
	v_add_u32_e32 v3, s6, v211
	v_add_u32_e32 v2, s6, v165
	v_add_u32_e32 v0, s6, v212
	v_cmp_lt_u32_e64 s[44:45], s77, v91
	v_cmp_lt_u32_e64 s[40:41], s77, v90
	v_cmp_lt_u32_e64 s[42:43], s77, v89
	v_cmp_lt_u32_e64 s[30:31], s77, v88
	v_cmp_lt_u32_e64 s[34:35], s77, v87
	v_cmp_lt_u32_e64 s[36:37], s77, v86
	v_cmp_lt_u32_e64 s[38:39], s77, v85
	s_cbranch_vccz .LBB0_1235
	ds_read_b128 v[134:137], v84
	ds_read_b128 v[138:141], v3
	ds_read_b128 v[142:145], v2
	ds_read_b128 v[170:173], v0
	ds_read_b128 v[174:177], v84 offset:4096
	ds_read_b128 v[182:185], v3 offset:4096
	ds_read_b128 v[186:189], v2 offset:4096
	ds_read_b128 v[206:209], v0 offset:4096
	s_waitcnt lgkmcnt(8)
	s_nop 0
	v_cndmask_b32_e64 v36, v92, 0, s[28:29]
	v_xor_b32_e32 v38, 0x80000000, v36
	v_mov_b32_e32 v39, v38
	v_mov_b32_e32 v40, v38
	v_mov_b32_e32 v41, v38
	v_add_u32_e32 v37, -4, v110
	s_movk_i32 s7, 0x200
	s_nop 0
	s_waitcnt lgkmcnt(7)
	v_mfma_f32_16x16x32_bf16 v[42:45], v[134:137], v[4:7], v[38:41]
	v_cmp_gt_u32_e32 vcc, s7, v37
	v_add_u32_e32 v37, 0xfffffdf8, v110
	s_nop 0
	s_waitcnt lgkmcnt(6)
	v_mfma_f32_16x16x32_bf16 v[42:45], v[138:141], v[8:11], v[42:45]
	s_nop 0
	s_nop 0
	s_nop 0
	s_waitcnt lgkmcnt(5)
	v_mfma_f32_16x16x32_bf16 v[46:49], v[142:145], v[4:7], v[38:41]
	s_nop 0
	s_waitcnt lgkmcnt(4)
	v_mfma_f32_16x16x32_bf16 v[46:49], v[170:173], v[8:11], v[46:49]
	s_nop 0
	s_nop 0
	s_nop 0
	s_waitcnt lgkmcnt(3)
	v_mfma_f32_16x16x32_bf16 v[50:53], v[174:177], v[4:7], v[38:41]
	s_nop 0
	s_waitcnt lgkmcnt(2)
	v_mfma_f32_16x16x32_bf16 v[60:63], v[182:185], v[8:11], v[50:53]
	s_nop 5
	s_nop 0
	s_nop 0
	v_cndmask_b32_e64 v61, v201, v61, s[34:35]
	s_nop 0
	s_waitcnt lgkmcnt(1)
	v_mfma_f32_16x16x32_bf16 v[38:41], v[186:189], v[4:7], v[38:41]
	v_cndmask_b32_e32 v52, v201, v42, vcc
	v_cmp_lt_u32_e32 vcc, s77, v37
	v_add_u32_e32 v37, 0xfffffdf7, v110
	s_nop 0
	s_waitcnt lgkmcnt(0)
	v_mfma_f32_16x16x32_bf16 v[38:41], v[206:209], v[8:11], v[38:41]
	v_cndmask_b32_e32 v56, v201, v46, vcc
	v_cmp_lt_u32_e32 vcc, s77, v37
	v_add_u32_e32 v37, 0xfffffdf6, v110
	v_cndmask_b32_e64 v54, v201, v44, s[40:41]
	v_cndmask_b32_e32 v57, v201, v47, vcc
	v_cmp_lt_u32_e32 vcc, s77, v37
	v_add_u32_e32 v37, 0xfffffdf5, v110
	v_cndmask_b32_e64 v55, v201, v45, s[42:43]
	v_cndmask_b32_e32 v58, v201, v48, vcc
	v_cmp_lt_u32_e32 vcc, s77, v37
	v_add_u32_e32 v37, 0xfffffdd8, v110
	v_cndmask_b32_e64 v53, v201, v43, s[44:45]
	v_cndmask_b32_e32 v59, v201, v49, vcc
	v_cmp_lt_u32_e32 vcc, s77, v37
	v_add_u32_e32 v37, 0xfffffdd7, v110
	v_cndmask_b32_e64 v62, v201, v62, s[36:37]
	v_cndmask_b32_e32 v64, v201, v38, vcc
	v_cmp_lt_u32_e32 vcc, s77, v37
	v_add_u32_e32 v37, 0xfffffdd6, v110
	v_max_f32_e32 v38, v54, v54
	v_cndmask_b32_e32 v65, v201, v39, vcc
	v_cmp_lt_u32_e32 vcc, s77, v37
	v_add_u32_e32 v37, 0xfffffdd5, v110
	v_cndmask_b32_e64 v63, v201, v63, s[38:39]
	v_cndmask_b32_e32 v66, v201, v40, vcc
	v_cmp_lt_u32_e32 vcc, s77, v37
	v_max_f32_e32 v37, v55, v55
	v_max_f32_e32 v37, v38, v37
	v_max3_f32 v37, v52, v53, v37
	v_max3_f32 v38, v57, v58, v59
	v_cndmask_b32_e64 v60, v201, v60, s[30:31]
	v_cndmask_b32_e32 v67, v201, v41, vcc
	v_max3_f32 v37, v37, v56, v38
	v_max3_f32 v38, v61, v62, v63
	v_max3_f32 v37, v37, v60, v38
	v_mov_b32_e32 v246, s76
	v_mov_b32_e32 v247, s82
	v_cndmask_b32_e64 v245, v247, v246, s[28:29]
	v_max3_f32 v38, v65, v66, v67
	v_max3_f32 v37, v37, v64, v38
	v_cmp_lt_f32_e32 vcc, v245, v37
	s_cbranch_vccz .LBB0_1247
	v_mov_b32_e32 v38, v37
	s_nop 1
	v_permlane16_swap_b32_e32 v37, v38
	v_max_f32_e32 v38, v38, v38
	v_max_f32_e32 v37, v37, v37
	v_max_f32_e32 v37, v37, v38
	v_mov_b32_e32 v38, v37
	s_nop 1
	v_permlane32_swap_b32_e32 v37, v38
	v_max_f32_e32 v38, v38, v38
	v_max_f32_e32 v37, v37, v37
	v_max_f32_e32 v37, v37, v38
	v_cmp_ge_f32_e32 vcc, s76, v37
	s_and_b64 vcc, s[28:29], vcc
	s_nop 0
	v_cndmask_b32_e64 v38, v37, 0, vcc
	v_max_f32_e32 v37, 0, v37
	v_cndmask_b32_e64 v123, v37, v38, s[28:29]
	v_exp_f32_e64 v96, -v123
	v_add_f32_e32 v36, v36, v123
	v_cndmask_b32_e32 v114, v36, v92, vcc
	v_sub_f32_e32 v95, v52, v123
	v_mul_f32_e32 v94, v93, v96
	v_pk_mul_f32 v[50:51], v[82:83], v[96:97] op_sel_hi:[1,0]
	v_pk_mul_f32 v[48:49], v[80:81], v[96:97] op_sel_hi:[1,0]
	v_pk_mul_f32 v[46:47], v[78:79], v[96:97] op_sel_hi:[1,0]
	v_pk_mul_f32 v[44:45], v[76:77], v[96:97] op_sel_hi:[1,0]
	v_pk_mul_f32 v[42:43], v[74:75], v[96:97] op_sel_hi:[1,0]
	v_pk_mul_f32 v[40:41], v[72:73], v[96:97] op_sel_hi:[1,0]
	v_pk_mul_f32 v[38:39], v[70:71], v[96:97] op_sel_hi:[1,0]
	v_pk_mul_f32 v[36:37], v[68:69], v[96:97] op_sel_hi:[1,0]
	v_sub_f32_e32 v96, v53, v123
	v_sub_f32_e32 v97, v54, v123
	v_sub_f32_e32 v98, v55, v123
	v_sub_f32_e32 v99, v56, v123
	v_sub_f32_e32 v108, v57, v123
	v_sub_f32_e32 v109, v58, v123
	v_sub_f32_e32 v115, v59, v123
	v_sub_f32_e32 v116, v60, v123
	v_sub_f32_e32 v117, v61, v123
	v_sub_f32_e32 v118, v62, v123
	v_sub_f32_e32 v119, v63, v123
	v_sub_f32_e32 v120, v64, v123
	v_sub_f32_e32 v121, v65, v123
	v_sub_f32_e32 v122, v66, v123
	v_sub_f32_e32 v123, v67, v123
	s_cbranch_execnz .LBB0_1227

.LBB0_1229:
	ds_read_b128 v[134:137], v84
	ds_read_b128 v[138:141], v3
	ds_read_b128 v[142:145], v2
	ds_read_b128 v[170:173], v0
	ds_read_b128 v[174:177], v84 offset:4096
	ds_read_b128 v[182:185], v3 offset:4096
	ds_read_b128 v[186:189], v2 offset:4096
	ds_read_b128 v[206:209], v0 offset:4096
	s_waitcnt lgkmcnt(8)
	s_nop 0
	s_nop 0
	s_nop 0
	v_cndmask_b32_e64 v68, v112, 0, s[28:29]
	v_xor_b32_e32 v78, 0x80000000, v68
	v_mov_b32_e32 v79, v78
	v_mov_b32_e32 v80, v78
	v_mov_b32_e32 v81, v78
	s_movk_i32 s7, 0x200
	v_cmp_gt_u32_e32 vcc, s7, v110
	s_nop 0
	s_waitcnt lgkmcnt(7)
	v_mfma_f32_16x16x32_bf16 v[70:73], v[134:137], v[12:15], v[78:81]
	v_add_u32_e32 v69, 0xfffffdff, v110
	s_nop 0
	s_waitcnt lgkmcnt(5)
	v_mfma_f32_16x16x32_bf16 v[74:77], v[142:145], v[12:15], v[78:81]
	s_nop 0
	v_mfma_f32_16x16x32_bf16 v[70:73], v[138:141], v[16:19], v[70:73]
	s_nop 0
	s_nop 0
	s_nop 0
	s_waitcnt lgkmcnt(4)
	v_mfma_f32_16x16x32_bf16 v[74:77], v[170:173], v[16:19], v[74:77]
	s_nop 0
	s_nop 0
	s_nop 0
	s_waitcnt lgkmcnt(3)
	v_mfma_f32_16x16x32_bf16 v[124:127], v[174:177], v[12:15], v[78:81]
	v_cndmask_b32_e32 v92, v201, v70, vcc
	v_cmp_lt_u32_e32 vcc, s77, v69
	v_add_u32_e32 v69, 0xfffffdfe, v110
	s_nop 0
	s_waitcnt lgkmcnt(2)
	v_mfma_f32_16x16x32_bf16 v[116:119], v[182:185], v[16:19], v[124:127]
	v_cndmask_b32_e32 v93, v201, v71, vcc
	v_cmp_lt_u32_e32 vcc, s77, v69
	v_add_u32_e32 v69, 0xfffffdfd, v110
	s_nop 0
	s_waitcnt lgkmcnt(1)
	v_mfma_f32_16x16x32_bf16 v[78:81], v[186:189], v[12:15], v[78:81]
	v_cndmask_b32_e32 v94, v201, v72, vcc
	v_cmp_lt_u32_e32 vcc, s77, v69
	v_add_u32_e32 v69, 0xfffffdfc, v110
	s_nop 0
	s_waitcnt lgkmcnt(0)
	v_mfma_f32_16x16x32_bf16 v[78:81], v[206:209], v[16:19], v[78:81]
	v_cndmask_b32_e32 v95, v201, v73, vcc
	v_cmp_lt_u32_e32 vcc, s77, v69
	v_add_u32_e32 v69, 0xfffffde0, v110
	v_max_f32_e32 v70, v94, v94
	v_cndmask_b32_e32 v96, v201, v74, vcc
	v_cmp_lt_u32_e32 vcc, s77, v91
	s_nop 1
	v_cndmask_b32_e32 v91, v201, v75, vcc
	v_cmp_lt_u32_e32 vcc, s77, v90
	s_nop 1
	v_cndmask_b32_e32 v90, v201, v76, vcc
	v_cmp_lt_u32_e32 vcc, s77, v89
	s_nop 1
	v_cndmask_b32_e32 v89, v201, v77, vcc
	v_cmp_lt_u32_e32 vcc, s77, v69
	v_add_u32_e32 v69, 0xfffffddf, v110
	s_nop 0
	v_cndmask_b32_e32 v97, v201, v116, vcc
	v_cmp_lt_u32_e32 vcc, s77, v69
	v_add_u32_e32 v69, 0xfffffdde, v110
	s_nop 0
	v_cndmask_b32_e32 v98, v201, v117, vcc
	v_cmp_lt_u32_e32 vcc, s77, v69
	v_add_u32_e32 v69, 0xfffffddd, v110
	s_nop 0
	v_cndmask_b32_e32 v99, v201, v118, vcc
	v_cmp_lt_u32_e32 vcc, s77, v69
	v_max_f32_e32 v69, v95, v95
	v_max_f32_e32 v69, v70, v69
	v_cndmask_b32_e32 v108, v201, v119, vcc
	v_cmp_lt_u32_e32 vcc, s77, v88
	v_max3_f32 v69, v92, v93, v69
	v_max3_f32 v70, v91, v90, v89
	v_cndmask_b32_e32 v88, v201, v78, vcc
	v_cmp_lt_u32_e32 vcc, s77, v87
	v_max3_f32 v69, v69, v96, v70
	v_max3_f32 v70, v98, v99, v108
	v_cndmask_b32_e32 v87, v201, v79, vcc
	v_cmp_lt_u32_e32 vcc, s77, v86
	v_max3_f32 v69, v69, v97, v70
	s_nop 0
	v_cndmask_b32_e32 v86, v201, v80, vcc
	v_cmp_lt_u32_e32 vcc, s77, v85
	s_nop 1
	v_cndmask_b32_e32 v85, v201, v81, vcc
	v_mov_b32_e32 v246, s76
	v_mov_b32_e32 v247, s82
	v_cndmask_b32_e64 v245, v247, v246, s[28:29]
	v_max3_f32 v70, v87, v86, v85
	v_max3_f32 v69, v69, v88, v70
	v_cmp_lt_f32_e32 vcc, v245, v69
	s_cbranch_vccz .LBB0_1248
	v_mov_b32_e32 v70, v69
	s_nop 1
	v_permlane16_swap_b32_e32 v69, v70
	v_max_f32_e32 v70, v70, v70
	v_max_f32_e32 v69, v69, v69
	v_max_f32_e32 v69, v69, v70
	v_mov_b32_e32 v70, v69
	s_nop 1
	v_permlane32_swap_b32_e32 v69, v70
	v_max_f32_e32 v70, v70, v70
	v_max_f32_e32 v69, v69, v69
	v_max_f32_e32 v69, v69, v70
	v_cmp_ge_f32_e32 vcc, s76, v69
	s_and_b64 vcc, s[28:29], vcc
	s_nop 0
	v_cndmask_b32_e64 v70, v69, 0, vcc
	v_max_f32_e32 v69, 0, v69
	v_cndmask_b32_e64 v132, v69, v70, s[28:29]
	v_exp_f32_e64 v118, -v132
	v_add_f32_e32 v68, v68, v132
	v_cndmask_b32_e32 v115, v68, v112, vcc
	v_sub_f32_e32 v117, v92, v132
	v_mul_f32_e32 v116, v113, v118
	v_pk_mul_f32 v[82:83], v[34:35], v[118:119] op_sel_hi:[1,0]
	v_pk_mul_f32 v[80:81], v[32:33], v[118:119] op_sel_hi:[1,0]
	v_pk_mul_f32 v[78:79], v[30:31], v[118:119] op_sel_hi:[1,0]
	v_pk_mul_f32 v[76:77], v[28:29], v[118:119] op_sel_hi:[1,0]
	v_pk_mul_f32 v[74:75], v[26:27], v[118:119] op_sel_hi:[1,0]
	v_pk_mul_f32 v[72:73], v[24:25], v[118:119] op_sel_hi:[1,0]
	v_pk_mul_f32 v[70:71], v[22:23], v[118:119] op_sel_hi:[1,0]
	v_pk_mul_f32 v[68:69], v[20:21], v[118:119] op_sel_hi:[1,0]
	v_sub_f32_e32 v118, v93, v132
	v_sub_f32_e32 v119, v94, v132
	v_sub_f32_e32 v120, v95, v132
	v_sub_f32_e32 v121, v96, v132
	v_sub_f32_e32 v122, v91, v132
	v_sub_f32_e32 v123, v90, v132
	v_sub_f32_e32 v124, v89, v132
	v_sub_f32_e32 v125, v97, v132
	v_sub_f32_e32 v126, v98, v132
	v_sub_f32_e32 v127, v99, v132
	v_sub_f32_e32 v128, v108, v132
	v_sub_f32_e32 v129, v88, v132
	v_sub_f32_e32 v130, v87, v132
	v_sub_f32_e32 v131, v86, v132
	v_sub_f32_e32 v132, v85, v132
	s_cbranch_execnz .LBB0_1232

.LBB0_1235:
	s_and_b64 vcc, exec, s[52:53]
	s_cbranch_vccz .LBB0_1228
	ds_read_b128 v[134:137], v84
	ds_read_b128 v[138:141], v3
	ds_read_b128 v[142:145], v2
	ds_read_b128 v[170:173], v0
	ds_read_b128 v[174:177], v84 offset:4096
	ds_read_b128 v[182:185], v3 offset:4096
	ds_read_b128 v[186:189], v2 offset:4096
	s_waitcnt lgkmcnt(7)
	s_nop 0
	v_cmp_ge_f32_e64 s[28:29], s76, v92
	s_nop 0
	s_nop 0
	v_cndmask_b32_e64 v36, v92, 0, s[28:29]
	v_xor_b32_e32 v46, 0x80000000, v36
	v_mov_b32_e32 v47, v46
	v_mov_b32_e32 v48, v46
	v_mov_b32_e32 v49, v46
	s_nop 0
	s_nop 0
	s_waitcnt lgkmcnt(6)
	v_mfma_f32_16x16x32_bf16 v[38:41], v[134:137], v[4:7], v[46:49]
	s_nop 0
	s_waitcnt lgkmcnt(5)
	v_mfma_f32_16x16x32_bf16 v[52:55], v[138:141], v[8:11], v[38:41]
	s_nop 0
	s_waitcnt lgkmcnt(4)
	v_mfma_f32_16x16x32_bf16 v[42:45], v[142:145], v[4:7], v[46:49]
	s_nop 3
	s_nop 0
	s_nop 0
	v_max_f32_e32 v37, v55, v55
	v_max_f32_e32 v50, v54, v54
	s_nop 0
	s_waitcnt lgkmcnt(3)
	v_mfma_f32_16x16x32_bf16 v[56:59], v[170:173], v[8:11], v[42:45]
	s_nop 2
	s_nop 0
	s_nop 0
	ds_read_b128 v[94:97], v0 offset:4096
	s_nop 0
	v_max_f32_e32 v37, v50, v37
	s_nop 0
	s_waitcnt lgkmcnt(3)
	v_mfma_f32_16x16x32_bf16 v[38:41], v[174:177], v[4:7], v[46:49]
	v_max3_f32 v37, v52, v53, v37
	s_nop 0
	s_waitcnt lgkmcnt(2)
	v_mfma_f32_16x16x32_bf16 v[60:63], v[182:185], v[8:11], v[38:41]
	v_max3_f32 v42, v57, v58, v59
	v_max3_f32 v37, v37, v56, v42
	s_nop 0
	s_waitcnt lgkmcnt(1)
	v_mfma_f32_16x16x32_bf16 v[38:41], v[186:189], v[4:7], v[46:49]
	s_nop 0
	s_waitcnt lgkmcnt(0)
	v_mfma_f32_16x16x32_bf16 v[64:67], v[94:97], v[8:11], v[38:41]
	s_nop 1
	v_max3_f32 v42, v61, v62, v63
	v_max3_f32 v37, v37, v60, v42
	s_nop 3
	v_mov_b32_e32 v246, s76
	v_mov_b32_e32 v247, s82
	v_cndmask_b32_e64 v245, v247, v246, s[28:29]
	v_max3_f32 v38, v65, v66, v67
	v_max3_f32 v37, v37, v64, v38
	v_cmp_lt_f32_e32 vcc, v245, v37
	s_cbranch_vccz .LBB0_1249
	v_mov_b32_e32 v38, v37
	s_nop 1
	v_permlane16_swap_b32_e32 v37, v38
	v_max_f32_e32 v38, v38, v38
	v_max_f32_e32 v37, v37, v37
	v_max_f32_e32 v37, v37, v38
	v_mov_b32_e32 v38, v37
	s_nop 1
	v_permlane32_swap_b32_e32 v37, v38
	v_max_f32_e32 v38, v38, v38
	v_max_f32_e32 v37, v37, v37
	v_max_f32_e32 v37, v37, v38
	v_cmp_ge_f32_e32 vcc, s76, v37
	s_and_b64 vcc, s[28:29], vcc
	s_nop 0
	v_cndmask_b32_e64 v38, v37, 0, vcc
	v_max_f32_e32 v37, 0, v37
	v_cndmask_b32_e64 v123, v37, v38, s[28:29]
	v_exp_f32_e64 v96, -v123
	v_add_f32_e32 v36, v36, v123
	v_cndmask_b32_e32 v114, v36, v92, vcc
	v_sub_f32_e32 v95, v52, v123
	v_mul_f32_e32 v94, v93, v96
	v_pk_mul_f32 v[50:51], v[82:83], v[96:97] op_sel_hi:[1,0]
	v_pk_mul_f32 v[48:49], v[80:81], v[96:97] op_sel_hi:[1,0]
	v_pk_mul_f32 v[46:47], v[78:79], v[96:97] op_sel_hi:[1,0]
	v_pk_mul_f32 v[44:45], v[76:77], v[96:97] op_sel_hi:[1,0]
	v_pk_mul_f32 v[42:43], v[74:75], v[96:97] op_sel_hi:[1,0]
	v_pk_mul_f32 v[40:41], v[72:73], v[96:97] op_sel_hi:[1,0]
	v_pk_mul_f32 v[38:39], v[70:71], v[96:97] op_sel_hi:[1,0]
	v_pk_mul_f32 v[36:37], v[68:69], v[96:97] op_sel_hi:[1,0]
	v_sub_f32_e32 v96, v53, v123
	v_sub_f32_e32 v97, v54, v123
	v_sub_f32_e32 v98, v55, v123
	v_sub_f32_e32 v99, v56, v123
	v_sub_f32_e32 v108, v57, v123
	v_sub_f32_e32 v109, v58, v123
	v_sub_f32_e32 v115, v59, v123
	v_sub_f32_e32 v116, v60, v123
	v_sub_f32_e32 v117, v61, v123
	v_sub_f32_e32 v118, v62, v123
	v_sub_f32_e32 v119, v63, v123
	v_sub_f32_e32 v120, v64, v123
	v_sub_f32_e32 v121, v65, v123
	v_sub_f32_e32 v122, v66, v123
	v_sub_f32_e32 v123, v67, v123
	s_cbranch_execnz .LBB0_1239

.LBB0_1240:
	s_and_b64 vcc, exec, s[30:31]
	s_cbranch_vccz .LBB0_1245
	ds_read_b128 v[134:137], v84
	ds_read_b128 v[138:141], v3
	ds_read_b128 v[142:145], v2
	ds_read_b128 v[170:173], v0
	ds_read_b128 v[174:177], v84 offset:4096
	ds_read_b128 v[182:185], v3 offset:4096
	ds_read_b128 v[186:189], v2 offset:4096
	ds_read_b128 v[206:209], v0 offset:4096
	s_waitcnt lgkmcnt(8)
	s_nop 0
	v_cmp_ge_f32_e64 s[28:29], s76, v112
	s_nop 0
	s_nop 0
	v_cndmask_b32_e64 v85, v112, 0, s[28:29]
	v_xor_b32_e32 v80, 0x80000000, v85
	v_mov_b32_e32 v81, v80
	v_mov_b32_e32 v82, v80
	v_mov_b32_e32 v83, v80
	s_nop 0
	s_nop 0
	s_waitcnt lgkmcnt(7)
	v_mfma_f32_16x16x32_bf16 v[68:71], v[134:137], v[12:15], v[80:83]
	s_nop 0
	s_waitcnt lgkmcnt(6)
	v_mfma_f32_16x16x32_bf16 v[68:71], v[138:141], v[16:19], v[68:71]
	s_nop 0
	s_nop 0
	s_waitcnt lgkmcnt(5)
	v_mfma_f32_16x16x32_bf16 v[72:75], v[142:145], v[12:15], v[80:83]
	s_nop 0
	s_waitcnt lgkmcnt(4)
	v_mfma_f32_16x16x32_bf16 v[72:75], v[170:173], v[16:19], v[72:75]
	s_nop 0
	s_nop 0
	s_nop 0
	v_max_f32_e32 v0, v71, v71
	s_nop 0
	s_waitcnt lgkmcnt(3)
	v_mfma_f32_16x16x32_bf16 v[76:79], v[174:177], v[12:15], v[80:83]
	v_max_f32_e32 v2, v70, v70
	v_max_f32_e32 v0, v2, v0
	v_max3_f32 v0, v68, v69, v0
	s_nop 0
	s_waitcnt lgkmcnt(1)
	v_mfma_f32_16x16x32_bf16 v[80:83], v[186:189], v[12:15], v[80:83]
	v_max3_f32 v2, v73, v74, v75
	v_max3_f32 v0, v0, v72, v2
	v_mfma_f32_16x16x32_bf16 v[76:79], v[182:185], v[16:19], v[76:79]
	s_nop 0
	s_waitcnt lgkmcnt(0)
	v_mfma_f32_16x16x32_bf16 v[80:83], v[206:209], v[16:19], v[80:83]
	s_nop 5
	v_max3_f32 v2, v77, v78, v79
	v_max3_f32 v0, v0, v76, v2
	v_mov_b32_e32 v246, s76
	v_mov_b32_e32 v247, s82
	v_cndmask_b32_e64 v245, v247, v246, s[28:29]
	v_max3_f32 v2, v81, v82, v83
	v_max3_f32 v0, v0, v80, v2
	v_cmp_lt_f32_e32 vcc, v245, v0
	s_cbranch_vccz .LBB0_1250
	v_mov_b32_e32 v2, v0
	s_nop 1
	v_permlane16_swap_b32_e32 v0, v2
	v_max_f32_e32 v2, v2, v2
	v_max_f32_e32 v0, v0, v0
	v_max_f32_e32 v0, v0, v2
	v_mov_b32_e32 v2, v0
	s_nop 1
	v_permlane32_swap_b32_e32 v0, v2
	v_max_f32_e32 v2, v2, v2
	v_max_f32_e32 v0, v0, v0
	v_max_f32_e32 v0, v0, v2
	v_cmp_ge_f32_e32 vcc, s76, v0
	s_and_b64 vcc, s[28:29], vcc
	s_nop 0
	v_cndmask_b32_e64 v2, v0, 0, vcc
	v_max_f32_e32 v0, 0, v0
	v_cndmask_b32_e64 v3, v0, v2, s[28:29]
	v_exp_f32_e64 v2, -v3
	v_add_f32_e32 v0, v85, v3
	v_cndmask_b32_e32 v115, v0, v112, vcc
	v_sub_f32_e32 v108, v68, v3
	v_mul_f32_e32 v0, v113, v2
	v_pk_mul_f32 v[86:87], v[34:35], v[2:3] op_sel_hi:[1,0]
	v_pk_mul_f32 v[84:85], v[32:33], v[2:3] op_sel_hi:[1,0]
	v_pk_mul_f32 v[90:91], v[30:31], v[2:3] op_sel_hi:[1,0]
	v_pk_mul_f32 v[88:89], v[28:29], v[2:3] op_sel_hi:[1,0]
	v_pk_mul_f32 v[98:99], v[26:27], v[2:3] op_sel_hi:[1,0]
	v_pk_mul_f32 v[96:97], v[24:25], v[2:3] op_sel_hi:[1,0]
	v_pk_mul_f32 v[94:95], v[22:23], v[2:3] op_sel_hi:[1,0]
	v_pk_mul_f32 v[92:93], v[20:21], v[2:3] op_sel_hi:[1,0]
	v_sub_f32_e32 v116, v69, v3
	v_sub_f32_e32 v117, v70, v3
	v_sub_f32_e32 v118, v71, v3
	v_sub_f32_e32 v119, v72, v3
	v_sub_f32_e32 v120, v73, v3
	v_sub_f32_e32 v121, v74, v3
	v_sub_f32_e32 v122, v75, v3
	v_sub_f32_e32 v123, v76, v3
	v_sub_f32_e32 v124, v77, v3
	v_sub_f32_e32 v125, v78, v3
	v_sub_f32_e32 v126, v79, v3
	v_sub_f32_e32 v127, v80, v3
	v_sub_f32_e32 v128, v81, v3
	v_sub_f32_e32 v2, v82, v3
	v_sub_f32_e32 v3, v83, v3
	s_cbranch_execnz .LBB0_1244
